# hand-written dilated-attention unit loops with all K/V tile loads hoisted (6 sites)
# speedup vs baseline: 1.0092x; 1.0092x over previous
.LBB0_314:
	s_mov_b64 exec, -1
	s_load_dwordx2 s[100:101], s[0:1], 0xf0
	s_mov_b32 s98, s97
	v_and_b32_e32 v240, 31, v206
	v_bfe_u32 v252, v206, 5, 1
	v_lshlrev_b32_e32 v241, 4, v252
	v_lshlrev_b32_e32 v253, 2, v252
	v_sub_u32_e32 v242, v240, v253
	v_mov_b32_e32 v243, 0xf149f2ca
	v_lshrrev_b32_e32 v200, 6, v206
	v_mul_u32_u24_e32 v200, 0x2400, v200
	v_mul_u32_u24_e32 v201, 0x240, v252
	v_lshl_add_u32 v250, v240, 1, v201
	v_add_u32_e32 v250, v250, v200
	v_mul_u32_u24_e32 v201, 72, v240
	v_lshl_add_u32 v251, v252, 3, v201
	v_add_u32_e32 v251, v251, v200
	s_waitcnt lgkmcnt(0)
.Ldil_p0L0_loop:
	s_and_b32 s4, s98, 127
	s_mov_b32 s5, 0
	s_lshr_b32 s6, s98, 10
	s_and_b32 s7, s98, 0x380
	s_lshl_b32 s99, s6, 12
	s_add_u32 s8, s99, s5
	s_sub_u32 s9, 4, s4
	s_max_i32 s9, s9, 0
	s_lshl_b32 s99, s4, 5
	v_add_u32_e32 v244, s99, v240
	s_lshl_b32 s99, s8, 10
	s_add_u32 s99, s99, s7
	s_add_u32 s54, s99, 0x16000000
	s_add_u32 s54, s100, s54
	s_addc_u32 s55, s101, 0
	s_add_u32 s50, s54, 0x2000000
	s_addc_u32 s51, s55, 0
	s_add_u32 s52, s50, 0x2000000
	s_addc_u32 s53, s51, 0
	v_lshl_add_u32 v252, v244, 10, v241
	global_load_dwordx4 v[128:131], v252, s[54:55]
	global_load_dwordx4 v[134:137], v252, s[54:55] offset:32
	global_load_dwordx4 v[144:147], v252, s[54:55] offset:64
	global_load_dwordx4 v[148:151], v252, s[54:55] offset:96
	s_max_u32 s99, s9, 0
	s_lshl_b32 s99, s99, 5
	s_addk_i32 s99, 0xff80
	v_add_u32_e32 v253, s99, v244
	v_lshl_add_u32 v245, v253, 10, v241
	global_load_dwordx4 v[0:3], v245, s[50:51]
	global_load_dwordx4 v[4:7], v245, s[50:51] offset:32
	global_load_dwordx4 v[8:11], v245, s[50:51] offset:64
	global_load_dwordx4 v[12:15], v245, s[50:51] offset:96
	s_max_u32 s99, s9, 1
	s_lshl_b32 s99, s99, 5
	s_addk_i32 s99, 0xff80
	v_add_u32_e32 v253, s99, v244
	v_lshl_add_u32 v246, v253, 10, v241
	global_load_dwordx4 v[16:19], v246, s[50:51]
	global_load_dwordx4 v[20:23], v246, s[50:51] offset:32
	global_load_dwordx4 v[24:27], v246, s[50:51] offset:64
	global_load_dwordx4 v[28:31], v246, s[50:51] offset:96
	s_max_u32 s99, s9, 2
	s_lshl_b32 s99, s99, 5
	s_addk_i32 s99, 0xff80
	v_add_u32_e32 v253, s99, v244
	v_lshl_add_u32 v247, v253, 10, v241
	global_load_dwordx4 v[32:35], v247, s[50:51]
	global_load_dwordx4 v[36:39], v247, s[50:51] offset:32
	global_load_dwordx4 v[40:43], v247, s[50:51] offset:64
	global_load_dwordx4 v[44:47], v247, s[50:51] offset:96
	s_max_u32 s99, s9, 3
	s_lshl_b32 s99, s99, 5
	s_addk_i32 s99, 0xff80
	v_add_u32_e32 v253, s99, v244
	v_lshl_add_u32 v248, v253, 10, v241
	global_load_dwordx4 v[48:51], v248, s[50:51]
	global_load_dwordx4 v[52:55], v248, s[50:51] offset:32
	global_load_dwordx4 v[56:59], v248, s[50:51] offset:64
	global_load_dwordx4 v[60:63], v248, s[50:51] offset:96
	s_max_u32 s99, s9, 4
	s_lshl_b32 s99, s99, 5
	s_addk_i32 s99, 0xff80
	v_add_u32_e32 v253, s99, v244
	v_lshl_add_u32 v249, v253, 10, v241
	global_load_dwordx4 v[64:67], v249, s[50:51]
	global_load_dwordx4 v[68:71], v249, s[50:51] offset:32
	global_load_dwordx4 v[72:75], v249, s[50:51] offset:64
	global_load_dwordx4 v[76:79], v249, s[50:51] offset:96
	s_lshl_b32 s99, s8, 5
	s_lshr_b32 s58, s7, 5
	s_add_u32 s99, s99, s58
	s_add_u32 s99, s99, 0x400000
	s_add_u32 s58, s100, s99
	s_addc_u32 s59, s101, 0
	s_add_u32 s60, s58, 0x100000
	s_addc_u32 s61, s59, 0
	v_lshlrev_b32_e32 v155, 5, v244
	s_lshl_b32 s99, s8, 11
	s_lshl_b32 s56, s7, 1
	s_add_u32 s99, s99, s56
	s_add_u32 s99, s99, 0x8000000
	s_add_u32 s56, s100, s99
	s_addc_u32 s57, s101, 0
	v_lshl_add_u32 v156, v244, 11, v241
	v_mov_b32_e32 v203, v243
	v_mov_b32_e32 v204, 0
	v_mov_b32_e32 v208, 0
	v_mov_b32_e32 v224, 0
	v_mov_b32_e32 v209, 0
	v_mov_b32_e32 v225, 0
	v_mov_b32_e32 v210, 0
	v_mov_b32_e32 v226, 0
	v_mov_b32_e32 v211, 0
	v_mov_b32_e32 v227, 0
	v_mov_b32_e32 v212, 0
	v_mov_b32_e32 v228, 0
	v_mov_b32_e32 v213, 0
	v_mov_b32_e32 v229, 0
	v_mov_b32_e32 v214, 0
	v_mov_b32_e32 v230, 0
	v_mov_b32_e32 v215, 0
	v_mov_b32_e32 v231, 0
	v_mov_b32_e32 v216, 0
	v_mov_b32_e32 v232, 0
	v_mov_b32_e32 v217, 0
	v_mov_b32_e32 v233, 0
	v_mov_b32_e32 v218, 0
	v_mov_b32_e32 v234, 0
	v_mov_b32_e32 v219, 0
	v_mov_b32_e32 v235, 0
	v_mov_b32_e32 v220, 0
	v_mov_b32_e32 v236, 0
	v_mov_b32_e32 v221, 0
	v_mov_b32_e32 v237, 0
	v_mov_b32_e32 v222, 0
	v_mov_b32_e32 v238, 0
	v_mov_b32_e32 v223, 0
	v_mov_b32_e32 v239, 0
	v_mov_b32_e32 v202, v243
	s_cmp_gt_u32 s9, 0
	s_cbranch_scc1 .Ldil_p0L0_kskip0
	s_waitcnt vmcnt(16)
	v_mfma_f32_32x32x16_bf16 v[80:95], v[0:3], v[128:131], 0
	v_mfma_f32_32x32x16_bf16 v[80:95], v[4:7], v[134:137], v[80:95]
	v_mfma_f32_32x32x16_bf16 v[80:95], v[8:11], v[144:147], v[80:95]
	v_mfma_f32_32x32x16_bf16 v[80:95], v[12:15], v[148:151], v[80:95]
	global_load_dwordx4 v[0:3], v245, s[52:53]
	global_load_dwordx4 v[4:7], v245, s[52:53] offset:32
	global_load_dwordx4 v[8:11], v245, s[52:53] offset:64
	global_load_dwordx4 v[12:15], v245, s[52:53] offset:96
	s_nop 7
	v_cmp_gt_i32_e64 s[34:35], v242, 0
	v_cmp_gt_i32_e64 s[36:37], v242, 1
	v_cmp_gt_i32_e64 s[38:39], v242, 2
	v_cmp_gt_i32_e64 s[40:41], v242, 3
	v_cndmask_b32_e64 v80, v80, v243, s[34:35]
	v_cndmask_b32_e64 v81, v81, v243, s[36:37]
	v_cndmask_b32_e64 v82, v82, v243, s[38:39]
	v_cndmask_b32_e64 v83, v83, v243, s[40:41]
	v_cmp_gt_i32_e64 s[34:35], v242, 8
	v_cmp_gt_i32_e64 s[36:37], v242, 9
	v_cmp_gt_i32_e64 s[38:39], v242, 10
	v_cmp_gt_i32_e64 s[40:41], v242, 11
	v_cndmask_b32_e64 v84, v84, v243, s[34:35]
	v_cndmask_b32_e64 v85, v85, v243, s[36:37]
	v_cndmask_b32_e64 v86, v86, v243, s[38:39]
	v_cndmask_b32_e64 v87, v87, v243, s[40:41]
	v_cmp_gt_i32_e64 s[34:35], v242, 16
	v_cmp_gt_i32_e64 s[36:37], v242, 17
	v_cmp_gt_i32_e64 s[38:39], v242, 18
	v_cmp_gt_i32_e64 s[40:41], v242, 19
	v_cndmask_b32_e64 v88, v88, v243, s[34:35]
	v_cndmask_b32_e64 v89, v89, v243, s[36:37]
	v_cndmask_b32_e64 v90, v90, v243, s[38:39]
	v_cndmask_b32_e64 v91, v91, v243, s[40:41]
	v_cmp_gt_i32_e64 s[34:35], v242, 24
	v_cmp_gt_i32_e64 s[36:37], v242, 25
	v_cmp_gt_i32_e64 s[38:39], v242, 26
	v_cmp_gt_i32_e64 s[40:41], v242, 27
	v_cndmask_b32_e64 v92, v92, v243, s[34:35]
	v_cndmask_b32_e64 v93, v93, v243, s[36:37]
	v_cndmask_b32_e64 v94, v94, v243, s[38:39]
	v_cndmask_b32_e64 v95, v95, v243, s[40:41]
	v_max3_f32 v202, v202, v80, v81
	v_max3_f32 v202, v202, v82, v83
	v_max3_f32 v202, v202, v84, v85
	v_max3_f32 v202, v202, v86, v87
	v_max3_f32 v202, v202, v88, v89
	v_max3_f32 v202, v202, v90, v91
	v_max3_f32 v202, v202, v92, v93
	v_max3_f32 v202, v202, v94, v95
	s_branch .Ldil_p0L0_kdone0
.Ldil_p0L0_kskip0:
	global_load_dwordx4 v[0:3], v245, s[52:53]
	global_load_dwordx4 v[4:7], v245, s[52:53] offset:32
	global_load_dwordx4 v[8:11], v245, s[52:53] offset:64
	global_load_dwordx4 v[12:15], v245, s[52:53] offset:96
.Ldil_p0L0_kdone0:
	s_cmp_gt_u32 s9, 1
	s_cbranch_scc1 .Ldil_p0L0_kskip1
	s_waitcnt vmcnt(16)
	v_mfma_f32_32x32x16_bf16 v[96:111], v[16:19], v[128:131], 0
	v_mfma_f32_32x32x16_bf16 v[96:111], v[20:23], v[134:137], v[96:111]
	v_mfma_f32_32x32x16_bf16 v[96:111], v[24:27], v[144:147], v[96:111]
	v_mfma_f32_32x32x16_bf16 v[96:111], v[28:31], v[148:151], v[96:111]
	global_load_dwordx4 v[16:19], v246, s[52:53]
	global_load_dwordx4 v[20:23], v246, s[52:53] offset:32
	global_load_dwordx4 v[24:27], v246, s[52:53] offset:64
	global_load_dwordx4 v[28:31], v246, s[52:53] offset:96
	s_nop 7
	v_max3_f32 v202, v202, v96, v97
	v_max3_f32 v202, v202, v98, v99
	v_max3_f32 v202, v202, v100, v101
	v_max3_f32 v202, v202, v102, v103
	v_max3_f32 v202, v202, v104, v105
	v_max3_f32 v202, v202, v106, v107
	v_max3_f32 v202, v202, v108, v109
	v_max3_f32 v202, v202, v110, v111
	s_branch .Ldil_p0L0_kdone1
.Ldil_p0L0_kskip1:
	global_load_dwordx4 v[16:19], v246, s[52:53]
	global_load_dwordx4 v[20:23], v246, s[52:53] offset:32
	global_load_dwordx4 v[24:27], v246, s[52:53] offset:64
	global_load_dwordx4 v[28:31], v246, s[52:53] offset:96
.Ldil_p0L0_kdone1:
	s_cmp_gt_u32 s9, 2
	s_cbranch_scc1 .Ldil_p0L0_kskip2
	s_waitcnt vmcnt(16)
	v_mfma_f32_32x32x16_bf16 v[112:127], v[32:35], v[128:131], 0
	v_mfma_f32_32x32x16_bf16 v[112:127], v[36:39], v[134:137], v[112:127]
	v_mfma_f32_32x32x16_bf16 v[112:127], v[40:43], v[144:147], v[112:127]
	v_mfma_f32_32x32x16_bf16 v[112:127], v[44:47], v[148:151], v[112:127]
	global_load_dwordx4 v[32:35], v247, s[52:53]
	global_load_dwordx4 v[36:39], v247, s[52:53] offset:32
	global_load_dwordx4 v[40:43], v247, s[52:53] offset:64
	global_load_dwordx4 v[44:47], v247, s[52:53] offset:96
	s_nop 7
	v_max3_f32 v202, v202, v112, v113
	v_max3_f32 v202, v202, v114, v115
	v_max3_f32 v202, v202, v116, v117
	v_max3_f32 v202, v202, v118, v119
	v_max3_f32 v202, v202, v120, v121
	v_max3_f32 v202, v202, v122, v123
	v_max3_f32 v202, v202, v124, v125
	v_max3_f32 v202, v202, v126, v127
	s_branch .Ldil_p0L0_kdone2
.Ldil_p0L0_kskip2:
	global_load_dwordx4 v[32:35], v247, s[52:53]
	global_load_dwordx4 v[36:39], v247, s[52:53] offset:32
	global_load_dwordx4 v[40:43], v247, s[52:53] offset:64
	global_load_dwordx4 v[44:47], v247, s[52:53] offset:96
.Ldil_p0L0_kdone2:
	s_cmp_gt_u32 s9, 3
	s_cbranch_scc1 .Ldil_p0L0_kskip3
	s_waitcnt vmcnt(16)
	v_mfma_f32_32x32x16_bf16 v[168:183], v[48:51], v[128:131], 0
	v_mfma_f32_32x32x16_bf16 v[168:183], v[52:55], v[134:137], v[168:183]
	v_mfma_f32_32x32x16_bf16 v[168:183], v[56:59], v[144:147], v[168:183]
	v_mfma_f32_32x32x16_bf16 v[168:183], v[60:63], v[148:151], v[168:183]
	global_load_dwordx4 v[48:51], v248, s[52:53]
	global_load_dwordx4 v[52:55], v248, s[52:53] offset:32
	global_load_dwordx4 v[56:59], v248, s[52:53] offset:64
	global_load_dwordx4 v[60:63], v248, s[52:53] offset:96
	s_nop 7
	v_max3_f32 v202, v202, v168, v169
	v_max3_f32 v202, v202, v170, v171
	v_max3_f32 v202, v202, v172, v173
	v_max3_f32 v202, v202, v174, v175
	v_max3_f32 v202, v202, v176, v177
	v_max3_f32 v202, v202, v178, v179
	v_max3_f32 v202, v202, v180, v181
	v_max3_f32 v202, v202, v182, v183
	s_branch .Ldil_p0L0_kdone3
.Ldil_p0L0_kskip3:
	global_load_dwordx4 v[48:51], v248, s[52:53]
	global_load_dwordx4 v[52:55], v248, s[52:53] offset:32
	global_load_dwordx4 v[56:59], v248, s[52:53] offset:64
	global_load_dwordx4 v[60:63], v248, s[52:53] offset:96
.Ldil_p0L0_kdone3:
	s_waitcnt vmcnt(16)
	v_mfma_f32_32x32x16_bf16 v[184:199], v[64:67], v[128:131], 0
	v_mfma_f32_32x32x16_bf16 v[184:199], v[68:71], v[134:137], v[184:199]
	v_mfma_f32_32x32x16_bf16 v[184:199], v[72:75], v[144:147], v[184:199]
	v_mfma_f32_32x32x16_bf16 v[184:199], v[76:79], v[148:151], v[184:199]
	global_load_dwordx4 v[64:67], v249, s[52:53]
	global_load_dwordx4 v[68:71], v249, s[52:53] offset:32
	global_load_dwordx4 v[72:75], v249, s[52:53] offset:64
	global_load_dwordx4 v[76:79], v249, s[52:53] offset:96
	s_nop 7
	v_cmp_lt_i32_e64 s[34:35], v242, 0
	v_cmp_lt_i32_e64 s[36:37], v242, 1
	v_cmp_lt_i32_e64 s[38:39], v242, 2
	v_cmp_lt_i32_e64 s[40:41], v242, 3
	v_cndmask_b32_e64 v184, v184, v243, s[34:35]
	v_cndmask_b32_e64 v185, v185, v243, s[36:37]
	v_cndmask_b32_e64 v186, v186, v243, s[38:39]
	v_cndmask_b32_e64 v187, v187, v243, s[40:41]
	v_cmp_lt_i32_e64 s[34:35], v242, 8
	v_cmp_lt_i32_e64 s[36:37], v242, 9
	v_cmp_lt_i32_e64 s[38:39], v242, 10
	v_cmp_lt_i32_e64 s[40:41], v242, 11
	v_cndmask_b32_e64 v188, v188, v243, s[34:35]
	v_cndmask_b32_e64 v189, v189, v243, s[36:37]
	v_cndmask_b32_e64 v190, v190, v243, s[38:39]
	v_cndmask_b32_e64 v191, v191, v243, s[40:41]
	v_cmp_lt_i32_e64 s[34:35], v242, 16
	v_cmp_lt_i32_e64 s[36:37], v242, 17
	v_cmp_lt_i32_e64 s[38:39], v242, 18
	v_cmp_lt_i32_e64 s[40:41], v242, 19
	v_cndmask_b32_e64 v192, v192, v243, s[34:35]
	v_cndmask_b32_e64 v193, v193, v243, s[36:37]
	v_cndmask_b32_e64 v194, v194, v243, s[38:39]
	v_cndmask_b32_e64 v195, v195, v243, s[40:41]
	v_cmp_lt_i32_e64 s[34:35], v242, 24
	v_cmp_lt_i32_e64 s[36:37], v242, 25
	v_cmp_lt_i32_e64 s[38:39], v242, 26
	v_cmp_lt_i32_e64 s[40:41], v242, 27
	v_cndmask_b32_e64 v196, v196, v243, s[34:35]
	v_cndmask_b32_e64 v197, v197, v243, s[36:37]
	v_cndmask_b32_e64 v198, v198, v243, s[38:39]
	v_cndmask_b32_e64 v199, v199, v243, s[40:41]
	v_max3_f32 v202, v202, v184, v185
	v_max3_f32 v202, v202, v186, v187
	v_max3_f32 v202, v202, v188, v189
	v_max3_f32 v202, v202, v190, v191
	v_max3_f32 v202, v202, v192, v193
	v_max3_f32 v202, v202, v194, v195
	v_max3_f32 v202, v202, v196, v197
	v_max3_f32 v202, v202, v198, v199
	v_mov_b32_e32 v252, v202
	s_nop 1
	v_permlane32_swap_b32_e32 v202, v252
	s_waitcnt vmcnt(20)
	v_max3_f32 v205, v203, v202, v252
	v_sub_f32_e32 v153, v203, v205
	v_exp_f32_e32 v153, v153
	v_mov_b32_e32 v154, 0
	s_cmp_gt_u32 s9, 0
	s_cbranch_scc1 .Ldil_p0L0_eskip0
	v_sub_f32_e32 v80, v80, v205
	v_sub_f32_e32 v81, v81, v205
	v_exp_f32_e32 v80, v80
	v_sub_f32_e32 v82, v82, v205
	v_exp_f32_e32 v81, v81
	v_add_f32_e32 v154, v154, v80
	v_sub_f32_e32 v83, v83, v205
	v_exp_f32_e32 v82, v82
	v_add_f32_e32 v154, v154, v81
	v_sub_f32_e32 v84, v84, v205
	v_exp_f32_e32 v83, v83
	v_add_f32_e32 v154, v154, v82
	v_sub_f32_e32 v85, v85, v205
	v_exp_f32_e32 v84, v84
	v_add_f32_e32 v154, v154, v83
	v_sub_f32_e32 v86, v86, v205
	v_exp_f32_e32 v85, v85
	v_add_f32_e32 v154, v154, v84
	v_sub_f32_e32 v87, v87, v205
	v_exp_f32_e32 v86, v86
	v_add_f32_e32 v154, v154, v85
	v_sub_f32_e32 v88, v88, v205
	v_exp_f32_e32 v87, v87
	v_add_f32_e32 v154, v154, v86
	v_sub_f32_e32 v89, v89, v205
	v_exp_f32_e32 v88, v88
	v_add_f32_e32 v154, v154, v87
	v_sub_f32_e32 v90, v90, v205
	v_exp_f32_e32 v89, v89
	v_add_f32_e32 v154, v154, v88
	v_sub_f32_e32 v91, v91, v205
	v_exp_f32_e32 v90, v90
	v_add_f32_e32 v154, v154, v89
	v_sub_f32_e32 v92, v92, v205
	v_exp_f32_e32 v91, v91
	v_add_f32_e32 v154, v154, v90
	v_sub_f32_e32 v93, v93, v205
	v_exp_f32_e32 v92, v92
	v_add_f32_e32 v154, v154, v91
	v_sub_f32_e32 v94, v94, v205
	v_exp_f32_e32 v93, v93
	v_add_f32_e32 v154, v154, v92
	v_sub_f32_e32 v95, v95, v205
	v_exp_f32_e32 v94, v94
	v_add_f32_e32 v154, v154, v93
	v_exp_f32_e32 v95, v95
	v_add_f32_e32 v154, v154, v94
	s_nop 0
	v_add_f32_e32 v154, v154, v95
.Ldil_p0L0_eskip0:
	s_cmp_gt_u32 s9, 1
	s_cbranch_scc1 .Ldil_p0L0_eskip1
	v_sub_f32_e32 v96, v96, v205
	v_sub_f32_e32 v97, v97, v205
	v_exp_f32_e32 v96, v96
	v_sub_f32_e32 v98, v98, v205
	v_exp_f32_e32 v97, v97
	v_add_f32_e32 v154, v154, v96
	v_sub_f32_e32 v99, v99, v205
	v_exp_f32_e32 v98, v98
	v_add_f32_e32 v154, v154, v97
	v_sub_f32_e32 v100, v100, v205
	v_exp_f32_e32 v99, v99
	v_add_f32_e32 v154, v154, v98
	v_sub_f32_e32 v101, v101, v205
	v_exp_f32_e32 v100, v100
	v_add_f32_e32 v154, v154, v99
	v_sub_f32_e32 v102, v102, v205
	v_exp_f32_e32 v101, v101
	v_add_f32_e32 v154, v154, v100
	v_sub_f32_e32 v103, v103, v205
	v_exp_f32_e32 v102, v102
	v_add_f32_e32 v154, v154, v101
	v_sub_f32_e32 v104, v104, v205
	v_exp_f32_e32 v103, v103
	v_add_f32_e32 v154, v154, v102
	v_sub_f32_e32 v105, v105, v205
	v_exp_f32_e32 v104, v104
	v_add_f32_e32 v154, v154, v103
	v_sub_f32_e32 v106, v106, v205
	v_exp_f32_e32 v105, v105
	v_add_f32_e32 v154, v154, v104
	v_sub_f32_e32 v107, v107, v205
	v_exp_f32_e32 v106, v106
	v_add_f32_e32 v154, v154, v105
	v_sub_f32_e32 v108, v108, v205
	v_exp_f32_e32 v107, v107
	v_add_f32_e32 v154, v154, v106
	v_sub_f32_e32 v109, v109, v205
	v_exp_f32_e32 v108, v108
	v_add_f32_e32 v154, v154, v107
	v_sub_f32_e32 v110, v110, v205
	v_exp_f32_e32 v109, v109
	v_add_f32_e32 v154, v154, v108
	v_sub_f32_e32 v111, v111, v205
	v_exp_f32_e32 v110, v110
	v_add_f32_e32 v154, v154, v109
	v_exp_f32_e32 v111, v111
	v_add_f32_e32 v154, v154, v110
	s_nop 0
	v_add_f32_e32 v154, v154, v111
.Ldil_p0L0_eskip1:
	s_cmp_gt_u32 s9, 2
	s_cbranch_scc1 .Ldil_p0L0_eskip2
	v_sub_f32_e32 v112, v112, v205
	v_sub_f32_e32 v113, v113, v205
	v_exp_f32_e32 v112, v112
	v_sub_f32_e32 v114, v114, v205
	v_exp_f32_e32 v113, v113
	v_add_f32_e32 v154, v154, v112
	v_sub_f32_e32 v115, v115, v205
	v_exp_f32_e32 v114, v114
	v_add_f32_e32 v154, v154, v113
	v_sub_f32_e32 v116, v116, v205
	v_exp_f32_e32 v115, v115
	v_add_f32_e32 v154, v154, v114
	v_sub_f32_e32 v117, v117, v205
	v_exp_f32_e32 v116, v116
	v_add_f32_e32 v154, v154, v115
	v_sub_f32_e32 v118, v118, v205
	v_exp_f32_e32 v117, v117
	v_add_f32_e32 v154, v154, v116
	v_sub_f32_e32 v119, v119, v205
	v_exp_f32_e32 v118, v118
	v_add_f32_e32 v154, v154, v117
	v_sub_f32_e32 v120, v120, v205
	v_exp_f32_e32 v119, v119
	v_add_f32_e32 v154, v154, v118
	v_sub_f32_e32 v121, v121, v205
	v_exp_f32_e32 v120, v120
	v_add_f32_e32 v154, v154, v119
	v_sub_f32_e32 v122, v122, v205
	v_exp_f32_e32 v121, v121
	v_add_f32_e32 v154, v154, v120
	v_sub_f32_e32 v123, v123, v205
	v_exp_f32_e32 v122, v122
	v_add_f32_e32 v154, v154, v121
	v_sub_f32_e32 v124, v124, v205
	v_exp_f32_e32 v123, v123
	v_add_f32_e32 v154, v154, v122
	v_sub_f32_e32 v125, v125, v205
	v_exp_f32_e32 v124, v124
	v_add_f32_e32 v154, v154, v123
	v_sub_f32_e32 v126, v126, v205
	v_exp_f32_e32 v125, v125
	v_add_f32_e32 v154, v154, v124
	v_sub_f32_e32 v127, v127, v205
	v_exp_f32_e32 v126, v126
	v_add_f32_e32 v154, v154, v125
	v_exp_f32_e32 v127, v127
	v_add_f32_e32 v154, v154, v126
	s_nop 0
	v_add_f32_e32 v154, v154, v127
.Ldil_p0L0_eskip2:
	s_cmp_gt_u32 s9, 3
	s_cbranch_scc1 .Ldil_p0L0_eskip3
	v_sub_f32_e32 v168, v168, v205
	v_sub_f32_e32 v169, v169, v205
	v_exp_f32_e32 v168, v168
	v_sub_f32_e32 v170, v170, v205
	v_exp_f32_e32 v169, v169
	v_add_f32_e32 v154, v154, v168
	v_sub_f32_e32 v171, v171, v205
	v_exp_f32_e32 v170, v170
	v_add_f32_e32 v154, v154, v169
	v_sub_f32_e32 v172, v172, v205
	v_exp_f32_e32 v171, v171
	v_add_f32_e32 v154, v154, v170
	v_sub_f32_e32 v173, v173, v205
	v_exp_f32_e32 v172, v172
	v_add_f32_e32 v154, v154, v171
	v_sub_f32_e32 v174, v174, v205
	v_exp_f32_e32 v173, v173
	v_add_f32_e32 v154, v154, v172
	v_sub_f32_e32 v175, v175, v205
	v_exp_f32_e32 v174, v174
	v_add_f32_e32 v154, v154, v173
	v_sub_f32_e32 v176, v176, v205
	v_exp_f32_e32 v175, v175
	v_add_f32_e32 v154, v154, v174
	v_sub_f32_e32 v177, v177, v205
	v_exp_f32_e32 v176, v176
	v_add_f32_e32 v154, v154, v175
	v_sub_f32_e32 v178, v178, v205
	v_exp_f32_e32 v177, v177
	v_add_f32_e32 v154, v154, v176
	v_sub_f32_e32 v179, v179, v205
	v_exp_f32_e32 v178, v178
	v_add_f32_e32 v154, v154, v177
	v_sub_f32_e32 v180, v180, v205
	v_exp_f32_e32 v179, v179
	v_add_f32_e32 v154, v154, v178
	v_sub_f32_e32 v181, v181, v205
	v_exp_f32_e32 v180, v180
	v_add_f32_e32 v154, v154, v179
	v_sub_f32_e32 v182, v182, v205
	v_exp_f32_e32 v181, v181
	v_add_f32_e32 v154, v154, v180
	v_sub_f32_e32 v183, v183, v205
	v_exp_f32_e32 v182, v182
	v_add_f32_e32 v154, v154, v181
	v_exp_f32_e32 v183, v183
	v_add_f32_e32 v154, v154, v182
	s_nop 0
	v_add_f32_e32 v154, v154, v183
.Ldil_p0L0_eskip3:
	v_sub_f32_e32 v184, v184, v205
	v_sub_f32_e32 v185, v185, v205
	v_exp_f32_e32 v184, v184
	v_sub_f32_e32 v186, v186, v205
	v_exp_f32_e32 v185, v185
	v_add_f32_e32 v154, v154, v184
	v_sub_f32_e32 v187, v187, v205
	v_exp_f32_e32 v186, v186
	v_add_f32_e32 v154, v154, v185
	v_sub_f32_e32 v188, v188, v205
	v_exp_f32_e32 v187, v187
	v_add_f32_e32 v154, v154, v186
	v_sub_f32_e32 v189, v189, v205
	v_exp_f32_e32 v188, v188
	v_add_f32_e32 v154, v154, v187
	v_sub_f32_e32 v190, v190, v205
	v_exp_f32_e32 v189, v189
	v_add_f32_e32 v154, v154, v188
	v_sub_f32_e32 v191, v191, v205
	v_exp_f32_e32 v190, v190
	v_add_f32_e32 v154, v154, v189
	v_sub_f32_e32 v192, v192, v205
	v_exp_f32_e32 v191, v191
	v_add_f32_e32 v154, v154, v190
	v_sub_f32_e32 v193, v193, v205
	v_exp_f32_e32 v192, v192
	v_add_f32_e32 v154, v154, v191
	v_sub_f32_e32 v194, v194, v205
	v_exp_f32_e32 v193, v193
	v_add_f32_e32 v154, v154, v192
	v_sub_f32_e32 v195, v195, v205
	v_exp_f32_e32 v194, v194
	v_add_f32_e32 v154, v154, v193
	v_sub_f32_e32 v196, v196, v205
	v_exp_f32_e32 v195, v195
	v_add_f32_e32 v154, v154, v194
	v_sub_f32_e32 v197, v197, v205
	v_exp_f32_e32 v196, v196
	v_add_f32_e32 v154, v154, v195
	v_sub_f32_e32 v198, v198, v205
	v_exp_f32_e32 v197, v197
	v_add_f32_e32 v154, v154, v196
	v_sub_f32_e32 v199, v199, v205
	v_exp_f32_e32 v198, v198
	v_add_f32_e32 v154, v154, v197
	v_exp_f32_e32 v199, v199
	v_add_f32_e32 v154, v154, v198
	s_nop 0
	v_add_f32_e32 v154, v154, v199
	v_mov_b32_e32 v252, v154
	s_nop 1
	v_permlane32_swap_b32_e32 v154, v252
	s_nop 1
	v_add_f32_e32 v154, v154, v252
	v_fmac_f32_e32 v154, v204, v153
	s_cmp_gt_u32 s9, 0
	s_cbranch_scc1 .Ldil_p0L0_pskip0
	s_waitcnt vmcnt(16)
	ds_write_b16 v250, v0
	ds_write_b16_d16_hi v250, v0 offset:72
	ds_write_b16 v250, v1 offset:144
	ds_write_b16_d16_hi v250, v1 offset:216
	ds_write_b16 v250, v2 offset:288
	ds_write_b16_d16_hi v250, v2 offset:360
	ds_write_b16 v250, v3 offset:432
	ds_write_b16_d16_hi v250, v3 offset:504
	ds_write_b16 v250, v4 offset:1152
	ds_write_b16_d16_hi v250, v4 offset:1224
	ds_write_b16 v250, v5 offset:1296
	ds_write_b16_d16_hi v250, v5 offset:1368
	ds_write_b16 v250, v6 offset:1440
	ds_write_b16_d16_hi v250, v6 offset:1512
	ds_write_b16 v250, v7 offset:1584
	ds_write_b16_d16_hi v250, v7 offset:1656
	ds_write_b16 v250, v8 offset:2304
	ds_write_b16_d16_hi v250, v8 offset:2376
	ds_write_b16 v250, v9 offset:2448
	ds_write_b16_d16_hi v250, v9 offset:2520
	ds_write_b16 v250, v10 offset:2592
	ds_write_b16_d16_hi v250, v10 offset:2664
	ds_write_b16 v250, v11 offset:2736
	ds_write_b16_d16_hi v250, v11 offset:2808
	ds_write_b16 v250, v12 offset:3456
	ds_write_b16_d16_hi v250, v12 offset:3528
	ds_write_b16 v250, v13 offset:3600
	ds_write_b16_d16_hi v250, v13 offset:3672
	ds_write_b16 v250, v14 offset:3744
	ds_write_b16_d16_hi v250, v14 offset:3816
	ds_write_b16 v250, v15 offset:3888
	ds_write_b16_d16_hi v250, v15 offset:3960
	v_cvt_pk_bf16_f32 v158, v80, v81
	v_cvt_pk_bf16_f32 v159, v82, v83
	v_cvt_pk_bf16_f32 v160, v84, v85
	v_cvt_pk_bf16_f32 v161, v86, v87
	v_cvt_pk_bf16_f32 v162, v88, v89
	v_cvt_pk_bf16_f32 v163, v90, v91
	v_cvt_pk_bf16_f32 v164, v92, v93
	v_cvt_pk_bf16_f32 v165, v94, v95
	v_add_u32_e32 v253, 0, v251
	v_add_u32_e32 v200, 2304, v251
	s_waitcnt lgkmcnt(0)
	ds_read2_b64 v[128:131], v253 offset0:0 offset1:2
	ds_read2_b64 v[134:137], v200 offset0:0 offset1:2
	ds_read2_b64 v[144:147], v253 offset0:4 offset1:6
	ds_read2_b64 v[148:151], v200 offset0:4 offset1:6
	s_waitcnt lgkmcnt(0)
	v_mfma_f32_32x32x16_bf16 v[208:223], v[128:131], v[158:161], v[208:223]
	v_mfma_f32_32x32x16_bf16 v[224:239], v[134:137], v[158:161], v[224:239]
	v_mfma_f32_32x32x16_bf16 v[208:223], v[144:147], v[162:165], v[208:223]
	v_mfma_f32_32x32x16_bf16 v[224:239], v[148:151], v[162:165], v[224:239]
.Ldil_p0L0_pskip0:
	s_cmp_gt_u32 s9, 1
	s_cbranch_scc1 .Ldil_p0L0_pskip1
	s_waitcnt vmcnt(12)
	ds_write_b16 v250, v16 offset:4608
	ds_write_b16_d16_hi v250, v16 offset:4680
	ds_write_b16 v250, v17 offset:4752
	ds_write_b16_d16_hi v250, v17 offset:4824
	ds_write_b16 v250, v18 offset:4896
	ds_write_b16_d16_hi v250, v18 offset:4968
	ds_write_b16 v250, v19 offset:5040
	ds_write_b16_d16_hi v250, v19 offset:5112
	ds_write_b16 v250, v20 offset:5760
	ds_write_b16_d16_hi v250, v20 offset:5832
	ds_write_b16 v250, v21 offset:5904
	ds_write_b16_d16_hi v250, v21 offset:5976
	ds_write_b16 v250, v22 offset:6048
	ds_write_b16_d16_hi v250, v22 offset:6120
	ds_write_b16 v250, v23 offset:6192
	ds_write_b16_d16_hi v250, v23 offset:6264
	ds_write_b16 v250, v24 offset:6912
	ds_write_b16_d16_hi v250, v24 offset:6984
	ds_write_b16 v250, v25 offset:7056
	ds_write_b16_d16_hi v250, v25 offset:7128
	ds_write_b16 v250, v26 offset:7200
	ds_write_b16_d16_hi v250, v26 offset:7272
	ds_write_b16 v250, v27 offset:7344
	ds_write_b16_d16_hi v250, v27 offset:7416
	ds_write_b16 v250, v28 offset:8064
	ds_write_b16_d16_hi v250, v28 offset:8136
	ds_write_b16 v250, v29 offset:8208
	ds_write_b16_d16_hi v250, v29 offset:8280
	ds_write_b16 v250, v30 offset:8352
	ds_write_b16_d16_hi v250, v30 offset:8424
	ds_write_b16 v250, v31 offset:8496
	ds_write_b16_d16_hi v250, v31 offset:8568
	v_cvt_pk_bf16_f32 v158, v96, v97
	v_cvt_pk_bf16_f32 v159, v98, v99
	v_cvt_pk_bf16_f32 v160, v100, v101
	v_cvt_pk_bf16_f32 v161, v102, v103
	v_cvt_pk_bf16_f32 v162, v104, v105
	v_cvt_pk_bf16_f32 v163, v106, v107
	v_cvt_pk_bf16_f32 v164, v108, v109
	v_cvt_pk_bf16_f32 v165, v110, v111
	v_add_u32_e32 v253, 4608, v251
	v_add_u32_e32 v200, 6912, v251
	s_waitcnt lgkmcnt(0)
	ds_read2_b64 v[128:131], v253 offset0:0 offset1:2
	ds_read2_b64 v[134:137], v200 offset0:0 offset1:2
	ds_read2_b64 v[144:147], v253 offset0:4 offset1:6
	ds_read2_b64 v[148:151], v200 offset0:4 offset1:6
	s_waitcnt lgkmcnt(0)
	v_mfma_f32_32x32x16_bf16 v[208:223], v[128:131], v[158:161], v[208:223]
	v_mfma_f32_32x32x16_bf16 v[224:239], v[134:137], v[158:161], v[224:239]
	v_mfma_f32_32x32x16_bf16 v[208:223], v[144:147], v[162:165], v[208:223]
	v_mfma_f32_32x32x16_bf16 v[224:239], v[148:151], v[162:165], v[224:239]
.Ldil_p0L0_pskip1:
	s_cmp_gt_u32 s9, 2
	s_cbranch_scc1 .Ldil_p0L0_pskip2
	s_waitcnt vmcnt(8)
	ds_write_b16 v250, v32
	ds_write_b16_d16_hi v250, v32 offset:72
	ds_write_b16 v250, v33 offset:144
	ds_write_b16_d16_hi v250, v33 offset:216
	ds_write_b16 v250, v34 offset:288
	ds_write_b16_d16_hi v250, v34 offset:360
	ds_write_b16 v250, v35 offset:432
	ds_write_b16_d16_hi v250, v35 offset:504
	ds_write_b16 v250, v36 offset:1152
	ds_write_b16_d16_hi v250, v36 offset:1224
	ds_write_b16 v250, v37 offset:1296
	ds_write_b16_d16_hi v250, v37 offset:1368
	ds_write_b16 v250, v38 offset:1440
	ds_write_b16_d16_hi v250, v38 offset:1512
	ds_write_b16 v250, v39 offset:1584
	ds_write_b16_d16_hi v250, v39 offset:1656
	ds_write_b16 v250, v40 offset:2304
	ds_write_b16_d16_hi v250, v40 offset:2376
	ds_write_b16 v250, v41 offset:2448
	ds_write_b16_d16_hi v250, v41 offset:2520
	ds_write_b16 v250, v42 offset:2592
	ds_write_b16_d16_hi v250, v42 offset:2664
	ds_write_b16 v250, v43 offset:2736
	ds_write_b16_d16_hi v250, v43 offset:2808
	ds_write_b16 v250, v44 offset:3456
	ds_write_b16_d16_hi v250, v44 offset:3528
	ds_write_b16 v250, v45 offset:3600
	ds_write_b16_d16_hi v250, v45 offset:3672
	ds_write_b16 v250, v46 offset:3744
	ds_write_b16_d16_hi v250, v46 offset:3816
	ds_write_b16 v250, v47 offset:3888
	ds_write_b16_d16_hi v250, v47 offset:3960
	v_cvt_pk_bf16_f32 v158, v112, v113
	v_cvt_pk_bf16_f32 v159, v114, v115
	v_cvt_pk_bf16_f32 v160, v116, v117
	v_cvt_pk_bf16_f32 v161, v118, v119
	v_cvt_pk_bf16_f32 v162, v120, v121
	v_cvt_pk_bf16_f32 v163, v122, v123
	v_cvt_pk_bf16_f32 v164, v124, v125
	v_cvt_pk_bf16_f32 v165, v126, v127
	v_add_u32_e32 v253, 0, v251
	v_add_u32_e32 v200, 2304, v251
	s_waitcnt lgkmcnt(0)
	ds_read2_b64 v[128:131], v253 offset0:0 offset1:2
	ds_read2_b64 v[134:137], v200 offset0:0 offset1:2
	ds_read2_b64 v[144:147], v253 offset0:4 offset1:6
	ds_read2_b64 v[148:151], v200 offset0:4 offset1:6
	s_waitcnt lgkmcnt(0)
	v_mfma_f32_32x32x16_bf16 v[208:223], v[128:131], v[158:161], v[208:223]
	v_mfma_f32_32x32x16_bf16 v[224:239], v[134:137], v[158:161], v[224:239]
	v_mfma_f32_32x32x16_bf16 v[208:223], v[144:147], v[162:165], v[208:223]
	v_mfma_f32_32x32x16_bf16 v[224:239], v[148:151], v[162:165], v[224:239]
.Ldil_p0L0_pskip2:
	s_cmp_gt_u32 s9, 3
	s_cbranch_scc1 .Ldil_p0L0_pskip3
	s_waitcnt vmcnt(4)
	ds_write_b16 v250, v48 offset:4608
	ds_write_b16_d16_hi v250, v48 offset:4680
	ds_write_b16 v250, v49 offset:4752
	ds_write_b16_d16_hi v250, v49 offset:4824
	ds_write_b16 v250, v50 offset:4896
	ds_write_b16_d16_hi v250, v50 offset:4968
	ds_write_b16 v250, v51 offset:5040
	ds_write_b16_d16_hi v250, v51 offset:5112
	ds_write_b16 v250, v52 offset:5760
	ds_write_b16_d16_hi v250, v52 offset:5832
	ds_write_b16 v250, v53 offset:5904
	ds_write_b16_d16_hi v250, v53 offset:5976
	ds_write_b16 v250, v54 offset:6048
	ds_write_b16_d16_hi v250, v54 offset:6120
	ds_write_b16 v250, v55 offset:6192
	ds_write_b16_d16_hi v250, v55 offset:6264
	ds_write_b16 v250, v56 offset:6912
	ds_write_b16_d16_hi v250, v56 offset:6984
	ds_write_b16 v250, v57 offset:7056
	ds_write_b16_d16_hi v250, v57 offset:7128
	ds_write_b16 v250, v58 offset:7200
	ds_write_b16_d16_hi v250, v58 offset:7272
	ds_write_b16 v250, v59 offset:7344
	ds_write_b16_d16_hi v250, v59 offset:7416
	ds_write_b16 v250, v60 offset:8064
	ds_write_b16_d16_hi v250, v60 offset:8136
	ds_write_b16 v250, v61 offset:8208
	ds_write_b16_d16_hi v250, v61 offset:8280
	ds_write_b16 v250, v62 offset:8352
	ds_write_b16_d16_hi v250, v62 offset:8424
	ds_write_b16 v250, v63 offset:8496
	ds_write_b16_d16_hi v250, v63 offset:8568
	v_cvt_pk_bf16_f32 v158, v168, v169
	v_cvt_pk_bf16_f32 v159, v170, v171
	v_cvt_pk_bf16_f32 v160, v172, v173
	v_cvt_pk_bf16_f32 v161, v174, v175
	v_cvt_pk_bf16_f32 v162, v176, v177
	v_cvt_pk_bf16_f32 v163, v178, v179
	v_cvt_pk_bf16_f32 v164, v180, v181
	v_cvt_pk_bf16_f32 v165, v182, v183
	v_add_u32_e32 v253, 4608, v251
	v_add_u32_e32 v200, 6912, v251
	s_waitcnt lgkmcnt(0)
	ds_read2_b64 v[128:131], v253 offset0:0 offset1:2
	ds_read2_b64 v[134:137], v200 offset0:0 offset1:2
	ds_read2_b64 v[144:147], v253 offset0:4 offset1:6
	ds_read2_b64 v[148:151], v200 offset0:4 offset1:6
	s_waitcnt lgkmcnt(0)
	v_mfma_f32_32x32x16_bf16 v[208:223], v[128:131], v[158:161], v[208:223]
	v_mfma_f32_32x32x16_bf16 v[224:239], v[134:137], v[158:161], v[224:239]
	v_mfma_f32_32x32x16_bf16 v[208:223], v[144:147], v[162:165], v[208:223]
	v_mfma_f32_32x32x16_bf16 v[224:239], v[148:151], v[162:165], v[224:239]
.Ldil_p0L0_pskip3:
	s_waitcnt vmcnt(0)
	ds_write_b16 v250, v64
	ds_write_b16_d16_hi v250, v64 offset:72
	ds_write_b16 v250, v65 offset:144
	ds_write_b16_d16_hi v250, v65 offset:216
	ds_write_b16 v250, v66 offset:288
	ds_write_b16_d16_hi v250, v66 offset:360
	ds_write_b16 v250, v67 offset:432
	ds_write_b16_d16_hi v250, v67 offset:504
	ds_write_b16 v250, v68 offset:1152
	ds_write_b16_d16_hi v250, v68 offset:1224
	ds_write_b16 v250, v69 offset:1296
	ds_write_b16_d16_hi v250, v69 offset:1368
	ds_write_b16 v250, v70 offset:1440
	ds_write_b16_d16_hi v250, v70 offset:1512
	ds_write_b16 v250, v71 offset:1584
	ds_write_b16_d16_hi v250, v71 offset:1656
	ds_write_b16 v250, v72 offset:2304
	ds_write_b16_d16_hi v250, v72 offset:2376
	ds_write_b16 v250, v73 offset:2448
	ds_write_b16_d16_hi v250, v73 offset:2520
	ds_write_b16 v250, v74 offset:2592
	ds_write_b16_d16_hi v250, v74 offset:2664
	ds_write_b16 v250, v75 offset:2736
	ds_write_b16_d16_hi v250, v75 offset:2808
	ds_write_b16 v250, v76 offset:3456
	ds_write_b16_d16_hi v250, v76 offset:3528
	ds_write_b16 v250, v77 offset:3600
	ds_write_b16_d16_hi v250, v77 offset:3672
	ds_write_b16 v250, v78 offset:3744
	ds_write_b16_d16_hi v250, v78 offset:3816
	ds_write_b16 v250, v79 offset:3888
	ds_write_b16_d16_hi v250, v79 offset:3960
	v_cvt_pk_bf16_f32 v158, v184, v185
	v_cvt_pk_bf16_f32 v159, v186, v187
	v_cvt_pk_bf16_f32 v160, v188, v189
	v_cvt_pk_bf16_f32 v161, v190, v191
	v_cvt_pk_bf16_f32 v162, v192, v193
	v_cvt_pk_bf16_f32 v163, v194, v195
	v_cvt_pk_bf16_f32 v164, v196, v197
	v_cvt_pk_bf16_f32 v165, v198, v199
	v_add_u32_e32 v253, 0, v251
	v_add_u32_e32 v200, 2304, v251
	s_waitcnt lgkmcnt(0)
	ds_read2_b64 v[128:131], v253 offset0:0 offset1:2
	ds_read2_b64 v[134:137], v200 offset0:0 offset1:2
	ds_read2_b64 v[144:147], v253 offset0:4 offset1:6
	ds_read2_b64 v[148:151], v200 offset0:4 offset1:6
	s_waitcnt lgkmcnt(0)
	v_mfma_f32_32x32x16_bf16 v[208:223], v[128:131], v[158:161], v[208:223]
	v_mfma_f32_32x32x16_bf16 v[224:239], v[134:137], v[158:161], v[224:239]
	v_mfma_f32_32x32x16_bf16 v[208:223], v[144:147], v[162:165], v[208:223]
	v_mfma_f32_32x32x16_bf16 v[224:239], v[148:151], v[162:165], v[224:239]
	s_nop 7
	s_nop 3
	global_store_dwordx4 v156, v[208:211], s[56:57]
	global_store_dwordx4 v156, v[212:215], s[56:57] offset:32
	global_store_dwordx4 v156, v[216:219], s[56:57] offset:64
	global_store_dwordx4 v156, v[220:223], s[56:57] offset:96
	global_store_dwordx4 v156, v[224:227], s[56:57] offset:128
	global_store_dwordx4 v156, v[228:231], s[56:57] offset:160
	global_store_dwordx4 v156, v[232:235], s[56:57] offset:192
	global_store_dwordx4 v156, v[236:239], s[56:57] offset:224
	s_mov_b64 exec, 0xffffffff
	global_store_dword v155, v205, s[58:59]
	global_store_dword v155, v154, s[60:61]
	s_mov_b64 exec, -1
	s_lshl_b32 s99, s33, 3
	s_add_i32 s98, s98, s99
	s_cmpk_lt_i32 s98, 0x2000
	s_cbranch_scc1 .Ldil_p0L0_loop
	s_waitcnt lgkmcnt(0)
	s_branch .LBB0_348

.LBB0_410:
	s_mov_b64 exec, -1
	s_load_dwordx2 s[100:101], s[0:1], 0xf0
	s_mov_b32 s98, s94
	v_and_b32_e32 v240, 31, v206
	v_bfe_u32 v252, v206, 5, 1
	v_lshlrev_b32_e32 v241, 4, v252
	v_lshlrev_b32_e32 v253, 2, v252
	v_sub_u32_e32 v242, v240, v253
	v_mov_b32_e32 v243, 0xf149f2ca
	v_lshrrev_b32_e32 v200, 6, v206
	v_mul_u32_u24_e32 v200, 0x2400, v200
	v_mul_u32_u24_e32 v201, 0x240, v252
	v_lshl_add_u32 v250, v240, 1, v201
	v_add_u32_e32 v250, v250, v200
	v_mul_u32_u24_e32 v201, 72, v240
	v_lshl_add_u32 v251, v252, 3, v201
	v_add_u32_e32 v251, v251, v200
	s_waitcnt lgkmcnt(0)
.Ldil_p1L0_loop:
	s_and_b32 s4, s98, 31
	s_bfe_u32 s5, s98, 0x20005
	s_lshr_b32 s6, s98, 10
	s_and_b32 s7, s98, 0x380
	s_lshl_b32 s99, s6, 12
	s_add_u32 s8, s99, s5
	s_sub_u32 s9, 4, s4
	s_max_i32 s9, s9, 0
	s_lshl_b32 s99, s4, 5
	v_add_u32_e32 v244, s99, v240
	s_lshl_b32 s99, s8, 10
	s_add_u32 s99, s99, s7
	s_add_u32 s54, s99, 0x16000000
	s_add_u32 s54, s100, s54
	s_addc_u32 s55, s101, 0
	s_add_u32 s50, s54, 0x2000000
	s_addc_u32 s51, s55, 0
	s_add_u32 s52, s50, 0x2000000
	s_addc_u32 s53, s51, 0
	v_lshl_add_u32 v252, v244, 12, v241
	global_load_dwordx4 v[128:131], v252, s[54:55]
	global_load_dwordx4 v[134:137], v252, s[54:55] offset:32
	global_load_dwordx4 v[144:147], v252, s[54:55] offset:64
	global_load_dwordx4 v[148:151], v252, s[54:55] offset:96
	s_max_u32 s99, s9, 0
	s_lshl_b32 s99, s99, 5
	s_addk_i32 s99, 0xff80
	v_add_u32_e32 v253, s99, v244
	v_lshl_add_u32 v245, v253, 12, v241
	global_load_dwordx4 v[0:3], v245, s[50:51]
	global_load_dwordx4 v[4:7], v245, s[50:51] offset:32
	global_load_dwordx4 v[8:11], v245, s[50:51] offset:64
	global_load_dwordx4 v[12:15], v245, s[50:51] offset:96
	s_max_u32 s99, s9, 1
	s_lshl_b32 s99, s99, 5
	s_addk_i32 s99, 0xff80
	v_add_u32_e32 v253, s99, v244
	v_lshl_add_u32 v246, v253, 12, v241
	global_load_dwordx4 v[16:19], v246, s[50:51]
	global_load_dwordx4 v[20:23], v246, s[50:51] offset:32
	global_load_dwordx4 v[24:27], v246, s[50:51] offset:64
	global_load_dwordx4 v[28:31], v246, s[50:51] offset:96
	s_max_u32 s99, s9, 2
	s_lshl_b32 s99, s99, 5
	s_addk_i32 s99, 0xff80
	v_add_u32_e32 v253, s99, v244
	v_lshl_add_u32 v247, v253, 12, v241
	global_load_dwordx4 v[32:35], v247, s[50:51]
	global_load_dwordx4 v[36:39], v247, s[50:51] offset:32
	global_load_dwordx4 v[40:43], v247, s[50:51] offset:64
	global_load_dwordx4 v[44:47], v247, s[50:51] offset:96
	s_max_u32 s99, s9, 3
	s_lshl_b32 s99, s99, 5
	s_addk_i32 s99, 0xff80
	v_add_u32_e32 v253, s99, v244
	v_lshl_add_u32 v248, v253, 12, v241
	global_load_dwordx4 v[48:51], v248, s[50:51]
	global_load_dwordx4 v[52:55], v248, s[50:51] offset:32
	global_load_dwordx4 v[56:59], v248, s[50:51] offset:64
	global_load_dwordx4 v[60:63], v248, s[50:51] offset:96
	s_max_u32 s99, s9, 4
	s_lshl_b32 s99, s99, 5
	s_addk_i32 s99, 0xff80
	v_add_u32_e32 v253, s99, v244
	v_lshl_add_u32 v249, v253, 12, v241
	global_load_dwordx4 v[64:67], v249, s[50:51]
	global_load_dwordx4 v[68:71], v249, s[50:51] offset:32
	global_load_dwordx4 v[72:75], v249, s[50:51] offset:64
	global_load_dwordx4 v[76:79], v249, s[50:51] offset:96
	s_lshl_b32 s99, s8, 5
	s_lshr_b32 s58, s7, 5
	s_add_u32 s99, s99, s58
	s_add_u32 s99, s99, 0x400000
	s_add_u32 s58, s100, s99
	s_addc_u32 s59, s101, 0
	s_add_u32 s60, s58, 0x100000
	s_addc_u32 s61, s59, 0
	v_lshlrev_b32_e32 v155, 7, v244
	s_lshl_b32 s99, s8, 11
	s_lshl_b32 s56, s7, 1
	s_add_u32 s99, s99, s56
	s_add_u32 s99, s99, 0x8000000
	s_add_u32 s56, s100, s99
	s_addc_u32 s57, s101, 0
	v_lshl_add_u32 v156, v244, 13, v241
	global_load_dword v203, v155, s[58:59]
	global_load_dword v204, v155, s[60:61]
	global_load_dwordx4 v[208:211], v156, s[56:57]
	global_load_dwordx4 v[212:215], v156, s[56:57] offset:32
	global_load_dwordx4 v[216:219], v156, s[56:57] offset:64
	global_load_dwordx4 v[220:223], v156, s[56:57] offset:96
	global_load_dwordx4 v[224:227], v156, s[56:57] offset:128
	global_load_dwordx4 v[228:231], v156, s[56:57] offset:160
	global_load_dwordx4 v[232:235], v156, s[56:57] offset:192
	global_load_dwordx4 v[236:239], v156, s[56:57] offset:224
	v_mov_b32_e32 v202, v243
	s_cmp_gt_u32 s9, 0
	s_cbranch_scc1 .Ldil_p1L0_kskip0
	s_waitcnt vmcnt(26)
	v_mfma_f32_32x32x16_bf16 v[80:95], v[0:3], v[128:131], 0
	v_mfma_f32_32x32x16_bf16 v[80:95], v[4:7], v[134:137], v[80:95]
	v_mfma_f32_32x32x16_bf16 v[80:95], v[8:11], v[144:147], v[80:95]
	v_mfma_f32_32x32x16_bf16 v[80:95], v[12:15], v[148:151], v[80:95]
	global_load_dwordx4 v[0:3], v245, s[52:53]
	global_load_dwordx4 v[4:7], v245, s[52:53] offset:32
	global_load_dwordx4 v[8:11], v245, s[52:53] offset:64
	global_load_dwordx4 v[12:15], v245, s[52:53] offset:96
	s_nop 7
	v_cmp_gt_i32_e64 s[34:35], v242, 0
	v_cmp_gt_i32_e64 s[36:37], v242, 1
	v_cmp_gt_i32_e64 s[38:39], v242, 2
	v_cmp_gt_i32_e64 s[40:41], v242, 3
	v_cndmask_b32_e64 v80, v80, v243, s[34:35]
	v_cndmask_b32_e64 v81, v81, v243, s[36:37]
	v_cndmask_b32_e64 v82, v82, v243, s[38:39]
	v_cndmask_b32_e64 v83, v83, v243, s[40:41]
	v_cmp_gt_i32_e64 s[34:35], v242, 8
	v_cmp_gt_i32_e64 s[36:37], v242, 9
	v_cmp_gt_i32_e64 s[38:39], v242, 10
	v_cmp_gt_i32_e64 s[40:41], v242, 11
	v_cndmask_b32_e64 v84, v84, v243, s[34:35]
	v_cndmask_b32_e64 v85, v85, v243, s[36:37]
	v_cndmask_b32_e64 v86, v86, v243, s[38:39]
	v_cndmask_b32_e64 v87, v87, v243, s[40:41]
	v_cmp_gt_i32_e64 s[34:35], v242, 16
	v_cmp_gt_i32_e64 s[36:37], v242, 17
	v_cmp_gt_i32_e64 s[38:39], v242, 18
	v_cmp_gt_i32_e64 s[40:41], v242, 19
	v_cndmask_b32_e64 v88, v88, v243, s[34:35]
	v_cndmask_b32_e64 v89, v89, v243, s[36:37]
	v_cndmask_b32_e64 v90, v90, v243, s[38:39]
	v_cndmask_b32_e64 v91, v91, v243, s[40:41]
	v_cmp_gt_i32_e64 s[34:35], v242, 24
	v_cmp_gt_i32_e64 s[36:37], v242, 25
	v_cmp_gt_i32_e64 s[38:39], v242, 26
	v_cmp_gt_i32_e64 s[40:41], v242, 27
	v_cndmask_b32_e64 v92, v92, v243, s[34:35]
	v_cndmask_b32_e64 v93, v93, v243, s[36:37]
	v_cndmask_b32_e64 v94, v94, v243, s[38:39]
	v_cndmask_b32_e64 v95, v95, v243, s[40:41]
	v_max3_f32 v202, v202, v80, v81
	v_max3_f32 v202, v202, v82, v83
	v_max3_f32 v202, v202, v84, v85
	v_max3_f32 v202, v202, v86, v87
	v_max3_f32 v202, v202, v88, v89
	v_max3_f32 v202, v202, v90, v91
	v_max3_f32 v202, v202, v92, v93
	v_max3_f32 v202, v202, v94, v95
	s_branch .Ldil_p1L0_kdone0

.Ldil_p1L0_kdone0:
	s_cmp_gt_u32 s9, 1
	s_cbranch_scc1 .Ldil_p1L0_kskip1
	s_waitcnt vmcnt(26)
	v_mfma_f32_32x32x16_bf16 v[96:111], v[16:19], v[128:131], 0
	v_mfma_f32_32x32x16_bf16 v[96:111], v[20:23], v[134:137], v[96:111]
	v_mfma_f32_32x32x16_bf16 v[96:111], v[24:27], v[144:147], v[96:111]
	v_mfma_f32_32x32x16_bf16 v[96:111], v[28:31], v[148:151], v[96:111]
	global_load_dwordx4 v[16:19], v246, s[52:53]
	global_load_dwordx4 v[20:23], v246, s[52:53] offset:32
	global_load_dwordx4 v[24:27], v246, s[52:53] offset:64
	global_load_dwordx4 v[28:31], v246, s[52:53] offset:96
	s_nop 7
	v_max3_f32 v202, v202, v96, v97
	v_max3_f32 v202, v202, v98, v99
	v_max3_f32 v202, v202, v100, v101
	v_max3_f32 v202, v202, v102, v103
	v_max3_f32 v202, v202, v104, v105
	v_max3_f32 v202, v202, v106, v107
	v_max3_f32 v202, v202, v108, v109
	v_max3_f32 v202, v202, v110, v111
	s_branch .Ldil_p1L0_kdone1

.Ldil_p1L0_kdone1:
	s_cmp_gt_u32 s9, 2
	s_cbranch_scc1 .Ldil_p1L0_kskip2
	s_waitcnt vmcnt(26)
	v_mfma_f32_32x32x16_bf16 v[112:127], v[32:35], v[128:131], 0
	v_mfma_f32_32x32x16_bf16 v[112:127], v[36:39], v[134:137], v[112:127]
	v_mfma_f32_32x32x16_bf16 v[112:127], v[40:43], v[144:147], v[112:127]
	v_mfma_f32_32x32x16_bf16 v[112:127], v[44:47], v[148:151], v[112:127]
	global_load_dwordx4 v[32:35], v247, s[52:53]
	global_load_dwordx4 v[36:39], v247, s[52:53] offset:32
	global_load_dwordx4 v[40:43], v247, s[52:53] offset:64
	global_load_dwordx4 v[44:47], v247, s[52:53] offset:96
	s_nop 7
	v_max3_f32 v202, v202, v112, v113
	v_max3_f32 v202, v202, v114, v115
	v_max3_f32 v202, v202, v116, v117
	v_max3_f32 v202, v202, v118, v119
	v_max3_f32 v202, v202, v120, v121
	v_max3_f32 v202, v202, v122, v123
	v_max3_f32 v202, v202, v124, v125
	v_max3_f32 v202, v202, v126, v127
	s_branch .Ldil_p1L0_kdone2

.Ldil_p1L0_kdone2:
	s_cmp_gt_u32 s9, 3
	s_cbranch_scc1 .Ldil_p1L0_kskip3
	s_waitcnt vmcnt(26)
	v_mfma_f32_32x32x16_bf16 v[168:183], v[48:51], v[128:131], 0
	v_mfma_f32_32x32x16_bf16 v[168:183], v[52:55], v[134:137], v[168:183]
	v_mfma_f32_32x32x16_bf16 v[168:183], v[56:59], v[144:147], v[168:183]
	v_mfma_f32_32x32x16_bf16 v[168:183], v[60:63], v[148:151], v[168:183]
	global_load_dwordx4 v[48:51], v248, s[52:53]
	global_load_dwordx4 v[52:55], v248, s[52:53] offset:32
	global_load_dwordx4 v[56:59], v248, s[52:53] offset:64
	global_load_dwordx4 v[60:63], v248, s[52:53] offset:96
	s_nop 7
	v_max3_f32 v202, v202, v168, v169
	v_max3_f32 v202, v202, v170, v171
	v_max3_f32 v202, v202, v172, v173
	v_max3_f32 v202, v202, v174, v175
	v_max3_f32 v202, v202, v176, v177
	v_max3_f32 v202, v202, v178, v179
	v_max3_f32 v202, v202, v180, v181
	v_max3_f32 v202, v202, v182, v183
	s_branch .Ldil_p1L0_kdone3

.Ldil_p1L0_kdone3:
	s_waitcnt vmcnt(26)
	v_mfma_f32_32x32x16_bf16 v[184:199], v[64:67], v[128:131], 0
	v_mfma_f32_32x32x16_bf16 v[184:199], v[68:71], v[134:137], v[184:199]
	v_mfma_f32_32x32x16_bf16 v[184:199], v[72:75], v[144:147], v[184:199]
	v_mfma_f32_32x32x16_bf16 v[184:199], v[76:79], v[148:151], v[184:199]
	global_load_dwordx4 v[64:67], v249, s[52:53]
	global_load_dwordx4 v[68:71], v249, s[52:53] offset:32
	global_load_dwordx4 v[72:75], v249, s[52:53] offset:64
	global_load_dwordx4 v[76:79], v249, s[52:53] offset:96
	s_nop 7
	v_cmp_lt_i32_e64 s[34:35], v242, 0
	v_cmp_lt_i32_e64 s[36:37], v242, 1
	v_cmp_lt_i32_e64 s[38:39], v242, 2
	v_cmp_lt_i32_e64 s[40:41], v242, 3
	v_cndmask_b32_e64 v184, v184, v243, s[34:35]
	v_cndmask_b32_e64 v185, v185, v243, s[36:37]
	v_cndmask_b32_e64 v186, v186, v243, s[38:39]
	v_cndmask_b32_e64 v187, v187, v243, s[40:41]
	v_cmp_lt_i32_e64 s[34:35], v242, 8
	v_cmp_lt_i32_e64 s[36:37], v242, 9
	v_cmp_lt_i32_e64 s[38:39], v242, 10
	v_cmp_lt_i32_e64 s[40:41], v242, 11
	v_cndmask_b32_e64 v188, v188, v243, s[34:35]
	v_cndmask_b32_e64 v189, v189, v243, s[36:37]
	v_cndmask_b32_e64 v190, v190, v243, s[38:39]
	v_cndmask_b32_e64 v191, v191, v243, s[40:41]
	v_cmp_lt_i32_e64 s[34:35], v242, 16
	v_cmp_lt_i32_e64 s[36:37], v242, 17
	v_cmp_lt_i32_e64 s[38:39], v242, 18
	v_cmp_lt_i32_e64 s[40:41], v242, 19
	v_cndmask_b32_e64 v192, v192, v243, s[34:35]
	v_cndmask_b32_e64 v193, v193, v243, s[36:37]
	v_cndmask_b32_e64 v194, v194, v243, s[38:39]
	v_cndmask_b32_e64 v195, v195, v243, s[40:41]
	v_cmp_lt_i32_e64 s[34:35], v242, 24
	v_cmp_lt_i32_e64 s[36:37], v242, 25
	v_cmp_lt_i32_e64 s[38:39], v242, 26
	v_cmp_lt_i32_e64 s[40:41], v242, 27
	v_cndmask_b32_e64 v196, v196, v243, s[34:35]
	v_cndmask_b32_e64 v197, v197, v243, s[36:37]
	v_cndmask_b32_e64 v198, v198, v243, s[38:39]
	v_cndmask_b32_e64 v199, v199, v243, s[40:41]
	v_max3_f32 v202, v202, v184, v185
	v_max3_f32 v202, v202, v186, v187
	v_max3_f32 v202, v202, v188, v189
	v_max3_f32 v202, v202, v190, v191
	v_max3_f32 v202, v202, v192, v193
	v_max3_f32 v202, v202, v194, v195
	v_max3_f32 v202, v202, v196, v197
	v_max3_f32 v202, v202, v198, v199
	v_mov_b32_e32 v252, v202
	s_nop 1
	v_permlane32_swap_b32_e32 v202, v252
	s_waitcnt vmcnt(28)
	v_max3_f32 v205, v203, v202, v252
	v_sub_f32_e32 v153, v203, v205
	v_exp_f32_e32 v153, v153
	v_mov_b32_e32 v154, 0
	s_cmp_gt_u32 s9, 0
	s_cbranch_scc1 .Ldil_p1L0_eskip0
	v_sub_f32_e32 v80, v80, v205
	v_sub_f32_e32 v81, v81, v205
	v_exp_f32_e32 v80, v80
	v_sub_f32_e32 v82, v82, v205
	v_exp_f32_e32 v81, v81
	v_add_f32_e32 v154, v154, v80
	v_sub_f32_e32 v83, v83, v205
	v_exp_f32_e32 v82, v82
	v_add_f32_e32 v154, v154, v81
	v_sub_f32_e32 v84, v84, v205
	v_exp_f32_e32 v83, v83
	v_add_f32_e32 v154, v154, v82
	v_sub_f32_e32 v85, v85, v205
	v_exp_f32_e32 v84, v84
	v_add_f32_e32 v154, v154, v83
	v_sub_f32_e32 v86, v86, v205
	v_exp_f32_e32 v85, v85
	v_add_f32_e32 v154, v154, v84
	v_sub_f32_e32 v87, v87, v205
	v_exp_f32_e32 v86, v86
	v_add_f32_e32 v154, v154, v85
	v_sub_f32_e32 v88, v88, v205
	v_exp_f32_e32 v87, v87
	v_add_f32_e32 v154, v154, v86
	v_sub_f32_e32 v89, v89, v205
	v_exp_f32_e32 v88, v88
	v_add_f32_e32 v154, v154, v87
	v_sub_f32_e32 v90, v90, v205
	v_exp_f32_e32 v89, v89
	v_add_f32_e32 v154, v154, v88
	v_sub_f32_e32 v91, v91, v205
	v_exp_f32_e32 v90, v90
	v_add_f32_e32 v154, v154, v89
	v_sub_f32_e32 v92, v92, v205
	v_exp_f32_e32 v91, v91
	v_add_f32_e32 v154, v154, v90
	v_sub_f32_e32 v93, v93, v205
	v_exp_f32_e32 v92, v92
	v_add_f32_e32 v154, v154, v91
	v_sub_f32_e32 v94, v94, v205
	v_exp_f32_e32 v93, v93
	v_add_f32_e32 v154, v154, v92
	v_sub_f32_e32 v95, v95, v205
	v_exp_f32_e32 v94, v94
	v_add_f32_e32 v154, v154, v93
	v_exp_f32_e32 v95, v95
	v_add_f32_e32 v154, v154, v94
	s_nop 0
	v_add_f32_e32 v154, v154, v95

.Ldil_p1L0_eskip3:
	v_sub_f32_e32 v184, v184, v205
	v_sub_f32_e32 v185, v185, v205
	v_exp_f32_e32 v184, v184
	v_sub_f32_e32 v186, v186, v205
	v_exp_f32_e32 v185, v185
	v_add_f32_e32 v154, v154, v184
	v_sub_f32_e32 v187, v187, v205
	v_exp_f32_e32 v186, v186
	v_add_f32_e32 v154, v154, v185
	v_sub_f32_e32 v188, v188, v205
	v_exp_f32_e32 v187, v187
	v_add_f32_e32 v154, v154, v186
	v_sub_f32_e32 v189, v189, v205
	v_exp_f32_e32 v188, v188
	v_add_f32_e32 v154, v154, v187
	v_sub_f32_e32 v190, v190, v205
	v_exp_f32_e32 v189, v189
	v_add_f32_e32 v154, v154, v188
	v_sub_f32_e32 v191, v191, v205
	v_exp_f32_e32 v190, v190
	v_add_f32_e32 v154, v154, v189
	v_sub_f32_e32 v192, v192, v205
	v_exp_f32_e32 v191, v191
	v_add_f32_e32 v154, v154, v190
	v_sub_f32_e32 v193, v193, v205
	v_exp_f32_e32 v192, v192
	v_add_f32_e32 v154, v154, v191
	v_sub_f32_e32 v194, v194, v205
	v_exp_f32_e32 v193, v193
	v_add_f32_e32 v154, v154, v192
	v_sub_f32_e32 v195, v195, v205
	v_exp_f32_e32 v194, v194
	v_add_f32_e32 v154, v154, v193
	v_sub_f32_e32 v196, v196, v205
	v_exp_f32_e32 v195, v195
	v_add_f32_e32 v154, v154, v194
	v_sub_f32_e32 v197, v197, v205
	v_exp_f32_e32 v196, v196
	v_add_f32_e32 v154, v154, v195
	v_sub_f32_e32 v198, v198, v205
	v_exp_f32_e32 v197, v197
	v_add_f32_e32 v154, v154, v196
	v_sub_f32_e32 v199, v199, v205
	v_exp_f32_e32 v198, v198
	v_add_f32_e32 v154, v154, v197
	v_exp_f32_e32 v199, v199
	v_add_f32_e32 v154, v154, v198
	s_nop 0
	v_add_f32_e32 v154, v154, v199
	v_mov_b32_e32 v252, v154
	s_nop 1
	v_permlane32_swap_b32_e32 v154, v252
	s_nop 1
	v_add_f32_e32 v154, v154, v252
	v_fmac_f32_e32 v154, v204, v153
	s_waitcnt vmcnt(20)
	v_mul_f32_e32 v208, v208, v153
	v_mul_f32_e32 v224, v224, v153
	v_mul_f32_e32 v209, v209, v153
	v_mul_f32_e32 v225, v225, v153
	v_mul_f32_e32 v210, v210, v153
	v_mul_f32_e32 v226, v226, v153
	v_mul_f32_e32 v211, v211, v153
	v_mul_f32_e32 v227, v227, v153
	v_mul_f32_e32 v212, v212, v153
	v_mul_f32_e32 v228, v228, v153
	v_mul_f32_e32 v213, v213, v153
	v_mul_f32_e32 v229, v229, v153
	v_mul_f32_e32 v214, v214, v153
	v_mul_f32_e32 v230, v230, v153
	v_mul_f32_e32 v215, v215, v153
	v_mul_f32_e32 v231, v231, v153
	v_mul_f32_e32 v216, v216, v153
	v_mul_f32_e32 v232, v232, v153
	v_mul_f32_e32 v217, v217, v153
	v_mul_f32_e32 v233, v233, v153
	v_mul_f32_e32 v218, v218, v153
	v_mul_f32_e32 v234, v234, v153
	v_mul_f32_e32 v219, v219, v153
	v_mul_f32_e32 v235, v235, v153
	v_mul_f32_e32 v220, v220, v153
	v_mul_f32_e32 v236, v236, v153
	v_mul_f32_e32 v221, v221, v153
	v_mul_f32_e32 v237, v237, v153
	v_mul_f32_e32 v222, v222, v153
	v_mul_f32_e32 v238, v238, v153
	v_mul_f32_e32 v223, v223, v153
	v_mul_f32_e32 v239, v239, v153
	s_cmp_gt_u32 s9, 0
	s_cbranch_scc1 .Ldil_p1L0_pskip0
	s_waitcnt vmcnt(16)
	ds_write_b16 v250, v0
	ds_write_b16_d16_hi v250, v0 offset:72
	ds_write_b16 v250, v1 offset:144
	ds_write_b16_d16_hi v250, v1 offset:216
	ds_write_b16 v250, v2 offset:288
	ds_write_b16_d16_hi v250, v2 offset:360
	ds_write_b16 v250, v3 offset:432
	ds_write_b16_d16_hi v250, v3 offset:504
	ds_write_b16 v250, v4 offset:1152
	ds_write_b16_d16_hi v250, v4 offset:1224
	ds_write_b16 v250, v5 offset:1296
	ds_write_b16_d16_hi v250, v5 offset:1368
	ds_write_b16 v250, v6 offset:1440
	ds_write_b16_d16_hi v250, v6 offset:1512
	ds_write_b16 v250, v7 offset:1584
	ds_write_b16_d16_hi v250, v7 offset:1656
	ds_write_b16 v250, v8 offset:2304
	ds_write_b16_d16_hi v250, v8 offset:2376
	ds_write_b16 v250, v9 offset:2448
	ds_write_b16_d16_hi v250, v9 offset:2520
	ds_write_b16 v250, v10 offset:2592
	ds_write_b16_d16_hi v250, v10 offset:2664
	ds_write_b16 v250, v11 offset:2736
	ds_write_b16_d16_hi v250, v11 offset:2808
	ds_write_b16 v250, v12 offset:3456
	ds_write_b16_d16_hi v250, v12 offset:3528
	ds_write_b16 v250, v13 offset:3600
	ds_write_b16_d16_hi v250, v13 offset:3672
	ds_write_b16 v250, v14 offset:3744
	ds_write_b16_d16_hi v250, v14 offset:3816
	ds_write_b16 v250, v15 offset:3888
	ds_write_b16_d16_hi v250, v15 offset:3960
	v_cvt_pk_bf16_f32 v158, v80, v81
	v_cvt_pk_bf16_f32 v159, v82, v83
	v_cvt_pk_bf16_f32 v160, v84, v85
	v_cvt_pk_bf16_f32 v161, v86, v87
	v_cvt_pk_bf16_f32 v162, v88, v89
	v_cvt_pk_bf16_f32 v163, v90, v91
	v_cvt_pk_bf16_f32 v164, v92, v93
	v_cvt_pk_bf16_f32 v165, v94, v95
	v_add_u32_e32 v253, 0, v251
	v_add_u32_e32 v200, 2304, v251
	s_waitcnt lgkmcnt(0)
	ds_read2_b64 v[128:131], v253 offset0:0 offset1:2
	ds_read2_b64 v[134:137], v200 offset0:0 offset1:2
	ds_read2_b64 v[144:147], v253 offset0:4 offset1:6
	ds_read2_b64 v[148:151], v200 offset0:4 offset1:6
	s_waitcnt lgkmcnt(0)
	v_mfma_f32_32x32x16_bf16 v[208:223], v[128:131], v[158:161], v[208:223]
	v_mfma_f32_32x32x16_bf16 v[224:239], v[134:137], v[158:161], v[224:239]
	v_mfma_f32_32x32x16_bf16 v[208:223], v[144:147], v[162:165], v[208:223]
	v_mfma_f32_32x32x16_bf16 v[224:239], v[148:151], v[162:165], v[224:239]

.LBB0_499:
	s_mov_b64 exec, -1
	s_load_dwordx2 s[100:101], s[0:1], 0xf0
	s_mov_b32 s98, s8
	v_and_b32_e32 v240, 31, v206
	v_bfe_u32 v252, v206, 5, 1
	v_lshlrev_b32_e32 v241, 4, v252
	v_lshlrev_b32_e32 v253, 2, v252
	v_sub_u32_e32 v242, v240, v253
	v_mov_b32_e32 v243, 0xf149f2ca
	v_lshrrev_b32_e32 v200, 6, v206
	v_mul_u32_u24_e32 v200, 0x2400, v200
	v_mul_u32_u24_e32 v201, 0x240, v252
	v_lshl_add_u32 v250, v240, 1, v201
	v_add_u32_e32 v250, v250, v200
	v_mul_u32_u24_e32 v201, 72, v240
	v_lshl_add_u32 v251, v252, 3, v201
	v_add_u32_e32 v251, v251, v200
	s_waitcnt lgkmcnt(0)
.Ldil_p2L0_loop:
	s_and_b32 s4, s98, 7
	s_bfe_u32 s5, s98, 0x40003
	s_lshr_b32 s6, s98, 10
	s_and_b32 s7, s98, 0x380
	s_lshl_b32 s99, s6, 12
	s_add_u32 s8, s99, s5
	s_sub_u32 s9, 4, s4
	s_max_i32 s9, s9, 0
	s_lshl_b32 s99, s4, 5
	v_add_u32_e32 v244, s99, v240
	s_lshl_b32 s99, s8, 10
	s_add_u32 s99, s99, s7
	s_add_u32 s54, s99, 0x16000000
	s_add_u32 s54, s100, s54
	s_addc_u32 s55, s101, 0
	s_add_u32 s50, s54, 0x2000000
	s_addc_u32 s51, s55, 0
	s_add_u32 s52, s50, 0x2000000
	s_addc_u32 s53, s51, 0
	v_lshl_add_u32 v252, v244, 14, v241
	global_load_dwordx4 v[128:131], v252, s[54:55]
	global_load_dwordx4 v[134:137], v252, s[54:55] offset:32
	global_load_dwordx4 v[144:147], v252, s[54:55] offset:64
	global_load_dwordx4 v[148:151], v252, s[54:55] offset:96
	s_max_u32 s99, s9, 0
	s_lshl_b32 s99, s99, 5
	s_addk_i32 s99, 0xff80
	v_add_u32_e32 v253, s99, v244
	v_lshl_add_u32 v245, v253, 14, v241
	global_load_dwordx4 v[0:3], v245, s[50:51]
	global_load_dwordx4 v[4:7], v245, s[50:51] offset:32
	global_load_dwordx4 v[8:11], v245, s[50:51] offset:64
	global_load_dwordx4 v[12:15], v245, s[50:51] offset:96
	s_max_u32 s99, s9, 1
	s_lshl_b32 s99, s99, 5
	s_addk_i32 s99, 0xff80
	v_add_u32_e32 v253, s99, v244
	v_lshl_add_u32 v246, v253, 14, v241
	global_load_dwordx4 v[16:19], v246, s[50:51]
	global_load_dwordx4 v[20:23], v246, s[50:51] offset:32
	global_load_dwordx4 v[24:27], v246, s[50:51] offset:64
	global_load_dwordx4 v[28:31], v246, s[50:51] offset:96
	s_max_u32 s99, s9, 2
	s_lshl_b32 s99, s99, 5
	s_addk_i32 s99, 0xff80
	v_add_u32_e32 v253, s99, v244
	v_lshl_add_u32 v247, v253, 14, v241
	global_load_dwordx4 v[32:35], v247, s[50:51]
	global_load_dwordx4 v[36:39], v247, s[50:51] offset:32
	global_load_dwordx4 v[40:43], v247, s[50:51] offset:64
	global_load_dwordx4 v[44:47], v247, s[50:51] offset:96
	s_max_u32 s99, s9, 3
	s_lshl_b32 s99, s99, 5
	s_addk_i32 s99, 0xff80
	v_add_u32_e32 v253, s99, v244
	v_lshl_add_u32 v248, v253, 14, v241
	global_load_dwordx4 v[48:51], v248, s[50:51]
	global_load_dwordx4 v[52:55], v248, s[50:51] offset:32
	global_load_dwordx4 v[56:59], v248, s[50:51] offset:64
	global_load_dwordx4 v[60:63], v248, s[50:51] offset:96
	s_max_u32 s99, s9, 4
	s_lshl_b32 s99, s99, 5
	s_addk_i32 s99, 0xff80
	v_add_u32_e32 v253, s99, v244
	v_lshl_add_u32 v249, v253, 14, v241
	global_load_dwordx4 v[64:67], v249, s[50:51]
	global_load_dwordx4 v[68:71], v249, s[50:51] offset:32
	global_load_dwordx4 v[72:75], v249, s[50:51] offset:64
	global_load_dwordx4 v[76:79], v249, s[50:51] offset:96
	s_lshl_b32 s99, s8, 5
	s_lshr_b32 s58, s7, 5
	s_add_u32 s99, s99, s58
	s_add_u32 s99, s99, 0x400000
	s_add_u32 s58, s100, s99
	s_addc_u32 s59, s101, 0
	s_add_u32 s60, s58, 0x100000
	s_addc_u32 s61, s59, 0
	v_lshlrev_b32_e32 v155, 9, v244
	s_lshl_b32 s99, s8, 11
	s_lshl_b32 s56, s7, 1
	s_add_u32 s99, s99, s56
	s_add_u32 s99, s99, 0x8000000
	s_add_u32 s56, s100, s99
	s_addc_u32 s57, s101, 0
	v_lshl_add_u32 v156, v244, 15, v241
	global_load_dword v203, v155, s[58:59]
	global_load_dword v204, v155, s[60:61]
	global_load_dwordx4 v[208:211], v156, s[56:57]
	global_load_dwordx4 v[212:215], v156, s[56:57] offset:32
	global_load_dwordx4 v[216:219], v156, s[56:57] offset:64
	global_load_dwordx4 v[220:223], v156, s[56:57] offset:96
	global_load_dwordx4 v[224:227], v156, s[56:57] offset:128
	global_load_dwordx4 v[228:231], v156, s[56:57] offset:160
	global_load_dwordx4 v[232:235], v156, s[56:57] offset:192
	global_load_dwordx4 v[236:239], v156, s[56:57] offset:224
	s_lshl_b32 s99, s8, 11
	s_add_u32 s99, s99, s7
	s_add_u32 s99, s99, 0xc000400
	s_add_u32 s62, s100, s99
	s_addc_u32 s63, s101, 0
	v_lshrrev_b32_e32 v253, 1, v241
	v_lshl_add_u32 v157, v244, 15, v253
	v_mov_b32_e32 v202, v243
	s_cmp_gt_u32 s9, 0
	s_cbranch_scc1 .Ldil_p2L0_kskip0
	s_waitcnt vmcnt(26)
	v_mfma_f32_32x32x16_bf16 v[80:95], v[0:3], v[128:131], 0
	v_mfma_f32_32x32x16_bf16 v[80:95], v[4:7], v[134:137], v[80:95]
	v_mfma_f32_32x32x16_bf16 v[80:95], v[8:11], v[144:147], v[80:95]
	v_mfma_f32_32x32x16_bf16 v[80:95], v[12:15], v[148:151], v[80:95]
	global_load_dwordx4 v[0:3], v245, s[52:53]
	global_load_dwordx4 v[4:7], v245, s[52:53] offset:32
	global_load_dwordx4 v[8:11], v245, s[52:53] offset:64
	global_load_dwordx4 v[12:15], v245, s[52:53] offset:96
	s_nop 7
	v_cmp_gt_i32_e64 s[34:35], v242, 0
	v_cmp_gt_i32_e64 s[36:37], v242, 1
	v_cmp_gt_i32_e64 s[38:39], v242, 2
	v_cmp_gt_i32_e64 s[40:41], v242, 3
	v_cndmask_b32_e64 v80, v80, v243, s[34:35]
	v_cndmask_b32_e64 v81, v81, v243, s[36:37]
	v_cndmask_b32_e64 v82, v82, v243, s[38:39]
	v_cndmask_b32_e64 v83, v83, v243, s[40:41]
	v_cmp_gt_i32_e64 s[34:35], v242, 8
	v_cmp_gt_i32_e64 s[36:37], v242, 9
	v_cmp_gt_i32_e64 s[38:39], v242, 10
	v_cmp_gt_i32_e64 s[40:41], v242, 11
	v_cndmask_b32_e64 v84, v84, v243, s[34:35]
	v_cndmask_b32_e64 v85, v85, v243, s[36:37]
	v_cndmask_b32_e64 v86, v86, v243, s[38:39]
	v_cndmask_b32_e64 v87, v87, v243, s[40:41]
	v_cmp_gt_i32_e64 s[34:35], v242, 16
	v_cmp_gt_i32_e64 s[36:37], v242, 17
	v_cmp_gt_i32_e64 s[38:39], v242, 18
	v_cmp_gt_i32_e64 s[40:41], v242, 19
	v_cndmask_b32_e64 v88, v88, v243, s[34:35]
	v_cndmask_b32_e64 v89, v89, v243, s[36:37]
	v_cndmask_b32_e64 v90, v90, v243, s[38:39]
	v_cndmask_b32_e64 v91, v91, v243, s[40:41]
	v_cmp_gt_i32_e64 s[34:35], v242, 24
	v_cmp_gt_i32_e64 s[36:37], v242, 25
	v_cmp_gt_i32_e64 s[38:39], v242, 26
	v_cmp_gt_i32_e64 s[40:41], v242, 27
	v_cndmask_b32_e64 v92, v92, v243, s[34:35]
	v_cndmask_b32_e64 v93, v93, v243, s[36:37]
	v_cndmask_b32_e64 v94, v94, v243, s[38:39]
	v_cndmask_b32_e64 v95, v95, v243, s[40:41]
	v_max3_f32 v202, v202, v80, v81
	v_max3_f32 v202, v202, v82, v83
	v_max3_f32 v202, v202, v84, v85
	v_max3_f32 v202, v202, v86, v87
	v_max3_f32 v202, v202, v88, v89
	v_max3_f32 v202, v202, v90, v91
	v_max3_f32 v202, v202, v92, v93
	v_max3_f32 v202, v202, v94, v95
	s_branch .Ldil_p2L0_kdone0

.Ldil_p2L0_pskip3:
	s_waitcnt vmcnt(0)
	ds_write_b16 v250, v64
	ds_write_b16_d16_hi v250, v64 offset:72
	ds_write_b16 v250, v65 offset:144
	ds_write_b16_d16_hi v250, v65 offset:216
	ds_write_b16 v250, v66 offset:288
	ds_write_b16_d16_hi v250, v66 offset:360
	ds_write_b16 v250, v67 offset:432
	ds_write_b16_d16_hi v250, v67 offset:504
	ds_write_b16 v250, v68 offset:1152
	ds_write_b16_d16_hi v250, v68 offset:1224
	ds_write_b16 v250, v69 offset:1296
	ds_write_b16_d16_hi v250, v69 offset:1368
	ds_write_b16 v250, v70 offset:1440
	ds_write_b16_d16_hi v250, v70 offset:1512
	ds_write_b16 v250, v71 offset:1584
	ds_write_b16_d16_hi v250, v71 offset:1656
	ds_write_b16 v250, v72 offset:2304
	ds_write_b16_d16_hi v250, v72 offset:2376
	ds_write_b16 v250, v73 offset:2448
	ds_write_b16_d16_hi v250, v73 offset:2520
	ds_write_b16 v250, v74 offset:2592
	ds_write_b16_d16_hi v250, v74 offset:2664
	ds_write_b16 v250, v75 offset:2736
	ds_write_b16_d16_hi v250, v75 offset:2808
	ds_write_b16 v250, v76 offset:3456
	ds_write_b16_d16_hi v250, v76 offset:3528
	ds_write_b16 v250, v77 offset:3600
	ds_write_b16_d16_hi v250, v77 offset:3672
	ds_write_b16 v250, v78 offset:3744
	ds_write_b16_d16_hi v250, v78 offset:3816
	ds_write_b16 v250, v79 offset:3888
	ds_write_b16_d16_hi v250, v79 offset:3960
	v_cvt_pk_bf16_f32 v158, v184, v185
	v_cvt_pk_bf16_f32 v159, v186, v187
	v_cvt_pk_bf16_f32 v160, v188, v189
	v_cvt_pk_bf16_f32 v161, v190, v191
	v_cvt_pk_bf16_f32 v162, v192, v193
	v_cvt_pk_bf16_f32 v163, v194, v195
	v_cvt_pk_bf16_f32 v164, v196, v197
	v_cvt_pk_bf16_f32 v165, v198, v199
	v_add_u32_e32 v253, 0, v251
	v_add_u32_e32 v200, 2304, v251
	s_waitcnt lgkmcnt(0)
	ds_read2_b64 v[128:131], v253 offset0:0 offset1:2
	ds_read2_b64 v[134:137], v200 offset0:0 offset1:2
	ds_read2_b64 v[144:147], v253 offset0:4 offset1:6
	ds_read2_b64 v[148:151], v200 offset0:4 offset1:6
	s_waitcnt lgkmcnt(0)
	v_mfma_f32_32x32x16_bf16 v[208:223], v[128:131], v[158:161], v[208:223]
	v_mfma_f32_32x32x16_bf16 v[224:239], v[134:137], v[158:161], v[224:239]
	v_mfma_f32_32x32x16_bf16 v[208:223], v[144:147], v[162:165], v[208:223]
	v_mfma_f32_32x32x16_bf16 v[224:239], v[148:151], v[162:165], v[224:239]
	v_rcp_f32_e32 v252, v154
	s_nop 0
	v_fma_f32 v253, -v154, v252, 1.0
	v_fmac_f32_e32 v252, v253, v252
	s_nop 7
	v_mul_f32_e32 v208, v208, v252
	v_mul_f32_e32 v209, v209, v252
	v_mul_f32_e32 v210, v210, v252
	v_mul_f32_e32 v211, v211, v252
	v_cvt_pk_bf16_f32 v200, v208, v209
	v_cvt_pk_bf16_f32 v201, v210, v211
	global_store_dwordx2 v157, v[200:201], s[62:63]
	s_nop 0
	v_mul_f32_e32 v212, v212, v252
	v_mul_f32_e32 v213, v213, v252
	v_mul_f32_e32 v214, v214, v252
	v_mul_f32_e32 v215, v215, v252
	v_cvt_pk_bf16_f32 v200, v212, v213
	v_cvt_pk_bf16_f32 v201, v214, v215
	global_store_dwordx2 v157, v[200:201], s[62:63] offset:16
	s_nop 0
	v_mul_f32_e32 v216, v216, v252
	v_mul_f32_e32 v217, v217, v252
	v_mul_f32_e32 v218, v218, v252
	v_mul_f32_e32 v219, v219, v252
	v_cvt_pk_bf16_f32 v200, v216, v217
	v_cvt_pk_bf16_f32 v201, v218, v219
	global_store_dwordx2 v157, v[200:201], s[62:63] offset:32
	s_nop 0
	v_mul_f32_e32 v220, v220, v252
	v_mul_f32_e32 v221, v221, v252
	v_mul_f32_e32 v222, v222, v252
	v_mul_f32_e32 v223, v223, v252
	v_cvt_pk_bf16_f32 v200, v220, v221
	v_cvt_pk_bf16_f32 v201, v222, v223
	global_store_dwordx2 v157, v[200:201], s[62:63] offset:48
	s_nop 0
	v_mul_f32_e32 v224, v224, v252
	v_mul_f32_e32 v225, v225, v252
	v_mul_f32_e32 v226, v226, v252
	v_mul_f32_e32 v227, v227, v252
	v_cvt_pk_bf16_f32 v200, v224, v225
	v_cvt_pk_bf16_f32 v201, v226, v227
	global_store_dwordx2 v157, v[200:201], s[62:63] offset:64
	s_nop 0
	v_mul_f32_e32 v228, v228, v252
	v_mul_f32_e32 v229, v229, v252
	v_mul_f32_e32 v230, v230, v252
	v_mul_f32_e32 v231, v231, v252
	v_cvt_pk_bf16_f32 v200, v228, v229
	v_cvt_pk_bf16_f32 v201, v230, v231
	global_store_dwordx2 v157, v[200:201], s[62:63] offset:80
	s_nop 0
	v_mul_f32_e32 v232, v232, v252
	v_mul_f32_e32 v233, v233, v252
	v_mul_f32_e32 v234, v234, v252
	v_mul_f32_e32 v235, v235, v252
	v_cvt_pk_bf16_f32 v200, v232, v233
	v_cvt_pk_bf16_f32 v201, v234, v235
	global_store_dwordx2 v157, v[200:201], s[62:63] offset:96
	s_nop 0
	v_mul_f32_e32 v236, v236, v252
	v_mul_f32_e32 v237, v237, v252
	v_mul_f32_e32 v238, v238, v252
	v_mul_f32_e32 v239, v239, v252
	v_cvt_pk_bf16_f32 v200, v236, v237
	v_cvt_pk_bf16_f32 v201, v238, v239
	global_store_dwordx2 v157, v[200:201], s[62:63] offset:112
	s_nop 0
	s_lshl_b32 s99, s33, 3
	s_add_i32 s98, s98, s99
	s_cmpk_lt_i32 s98, 0x2000
	s_cbranch_scc1 .Ldil_p2L0_loop
	s_waitcnt lgkmcnt(0)
	s_branch .LBB0_530

	.amdhsa_kernel _ZN2mk3fwdENS_6ParamsE
		.amdhsa_group_segment_fixed_size 0
		.amdhsa_private_segment_fixed_size 0
		.amdhsa_kernarg_size 504
		.amdhsa_user_sgpr_count 2
		.amdhsa_user_sgpr_dispatch_ptr 0
		.amdhsa_user_sgpr_queue_ptr 0
		.amdhsa_user_sgpr_kernarg_segment_ptr 1
		.amdhsa_user_sgpr_dispatch_id 0
		.amdhsa_user_sgpr_kernarg_preload_length 0
		.amdhsa_user_sgpr_kernarg_preload_offset 0
		.amdhsa_user_sgpr_private_segment_size 0
		.amdhsa_uses_dynamic_stack 0
		.amdhsa_enable_private_segment 0
		.amdhsa_system_sgpr_workgroup_id_x 1
		.amdhsa_system_sgpr_workgroup_id_y 0
		.amdhsa_system_sgpr_workgroup_id_z 0
		.amdhsa_system_sgpr_workgroup_info 0
		.amdhsa_system_vgpr_workitem_id 2
		.amdhsa_next_free_vgpr 255
		.amdhsa_next_free_sgpr 102
		.amdhsa_accum_offset 256
		.amdhsa_reserve_vcc 1
		.amdhsa_float_round_mode_32 0
		.amdhsa_float_round_mode_16_64 0
		.amdhsa_float_denorm_mode_32 3
		.amdhsa_float_denorm_mode_16_64 3
		.amdhsa_dx10_clamp 1
		.amdhsa_ieee_mode 1
		.amdhsa_fp16_overflow 0
		.amdhsa_tg_split 0
		.amdhsa_exception_fp_ieee_invalid_op 0
		.amdhsa_exception_fp_denorm_src 0
		.amdhsa_exception_fp_ieee_div_zero 0
		.amdhsa_exception_fp_ieee_overflow 0
		.amdhsa_exception_fp_ieee_underflow 0
		.amdhsa_exception_fp_ieee_inexact 0
		.amdhsa_exception_int_div_zero 0
	.end_amdhsa_kernel

amdhsa.kernels:
  - .agpr_count:     0
    .args:
      - .offset:         0
        .size:           248
        .value_kind:     by_value
      - .offset:         248
        .size:           4
        .value_kind:     hidden_block_count_x
      - .offset:         252
        .size:           4
        .value_kind:     hidden_block_count_y
      - .offset:         256
        .size:           4
        .value_kind:     hidden_block_count_z
      - .offset:         260
        .size:           2
        .value_kind:     hidden_group_size_x
      - .offset:         262
        .size:           2
        .value_kind:     hidden_group_size_y
      - .offset:         264
        .size:           2
        .value_kind:     hidden_group_size_z
      - .offset:         266
        .size:           2
        .value_kind:     hidden_remainder_x
      - .offset:         268
        .size:           2
        .value_kind:     hidden_remainder_y
      - .offset:         270
        .size:           2
        .value_kind:     hidden_remainder_z
      - .offset:         288
        .size:           8
        .value_kind:     hidden_global_offset_x
      - .offset:         296
        .size:           8
        .value_kind:     hidden_global_offset_y
      - .offset:         304
        .size:           8
        .value_kind:     hidden_global_offset_z
      - .offset:         312
        .size:           2
        .value_kind:     hidden_grid_dims
      - .offset:         336
        .size:           8
        .value_kind:     hidden_multigrid_sync_arg
      - .offset:         368
        .size:           4
        .value_kind:     hidden_dynamic_lds_size
    .group_segment_fixed_size: 0
    .kernarg_segment_align: 8
    .kernarg_segment_size: 504
    .language:       OpenCL C
    .language_version:
      - 2
      - 0
    .max_flat_workgroup_size: 512
    .name:           _ZN2mk3fwdENS_6ParamsE
    .private_segment_fixed_size: 0
    .sgpr_count:     108
    .sgpr_spill_count: 33
    .symbol:         _ZN2mk3fwdENS_6ParamsE.kd
    .uniform_work_group_size: 1
    .uses_dynamic_stack: false
    .vgpr_count:     255
    .vgpr_spill_count: 0
    .wavefront_size: 64
